# attention: software-pipelined fast loop (QK/PV MFMAs interleaved under the other block's softmax VALU, double-buffered K/V register sets, P packed in place)
# speedup vs baseline: 1.0411x; 1.0114x over previous
; __device__ __forceinline__ void attn_phase(const bf16_t* Z, const bf16_t* Kb, const bf16_t* Vb, unsigned* MASKb, unsigned* itemcnt, bf16_t* Y, LAS unsigned char* lds, int wave, int lane, int bid, int G) {
;     ...
;             const size_t rowq = (size_t)b * SEQ + qb * 32 + ql;
;             const bf16_t* zq = Z + rowq * NZ + 1280 + h * 64 + hi * 8;
;             bf16x8 qf[4];
; #pragma unroll
;             for (int c = 0; c < 4; ++c) qf[c] = *(const bf16x8*)(zq + 16 * c);
;             unsigned* mrow = MASKb + ((size_t)(b * 128 + qb) * 128) * 32 + ql;
;             const bf16_t* kb = Kb + ((size_t)(b * 4 + h) * 128) * 2048 + ql * 16 + hi * 8;
;             const bf16_t* vb = Vb + ((size_t)(b * 4 + h) * 128) * 2048 + ql * 16 + hi * 8;
;             f32x16 o0, o1;
; #pragma unroll
;             for (int r = 0; r < 16; ++r) { o0[r] = 0.f; o1[r] = 0.f; }
;             float m = NEGF, l = 0.f;
;             bf16x8 kA[4], kB[4]; bf16x8 vA[2][2], vB[2][2]; unsigned mA = 0u, mB = 0u;
;     ...
;             if (tb < te) ATT_LOAD(kA, vA, mA, tb);
.Lat_nospin:
	s_barrier
	s_lshl_b32 s8, s18, 21
	s_or_b32 s8, s8, s24
	v_readlane_b32 s6, v255, 34
	v_readlane_b32 s7, v255, 35
	v_readlane_b32 s10, v255, 32
	v_readlane_b32 s11, v255, 33
	v_readlane_b32 s30, v255, 41
	v_readlane_b32 s31, v255, 42
	s_add_u32 s6, s6, s8
	s_addc_u32 s7, s7, 0
	s_add_u32 s10, s10, s8
	s_addc_u32 s11, s11, 0
	s_lshl_b32 s20, s18, 7
	s_lshl_b32 s21, s35, 1
	s_add_i32 s20, s20, s21
	s_lshl_b32 s20, s20, 14
	s_add_u32 s20, s30, s20
	s_addc_u32 s21, s31, 0
	s_add_i32 s19, s35, 1
	s_lshl_b32 s9, s19, 1
	s_and_b64 s[30:31], s[12:13], exec
	s_cselect_b32 s8, 0, s19
	s_cselect_b32 s19, s19, s9
	s_add_i32 s9, s19, -1
	s_lshl_b32 s35, s35, 1
	s_lshl_b32 s26, s18, 12
	s_lshl_b32 s34, s35, 5
	s_add_i32 s18, s34, s26
	v_or_b32_e32 v0, s18, v138
	v_mad_u64_u32 v[34:35], vcc, v0, s33, v[148:149]
	s_mov_b32 s30, 0x30000
	s_mov_b32 s31, 0
	global_load_dwordx4 v[82:85], v[34:35], off offset:2560
	global_load_dwordx4 v[86:89], v[34:35], off offset:2592
	global_load_dwordx4 v[90:93], v[34:35], off offset:2624
	global_load_dwordx4 v[94:97], v[34:35], off offset:2656
	v_lshl_add_u64 v[36:37], v[34:35], 0, s[30:31]
	global_load_dwordx4 v[114:117], v[36:37], off offset:2560
	global_load_dwordx4 v[118:121], v[36:37], off offset:2592
	global_load_dwordx4 v[122:125], v[36:37], off offset:2624
	global_load_dwordx4 v[126:129], v[36:37], off offset:2656
	v_lshlrev_b32_e32 v175, 2, v139
	v_lshl_add_u32 v175, v138, 5, v175
	v_lshlrev_b32_e32 v176, 2, v138
	v_add_u32_e32 v177, 0x4000, v176
	s_mov_b32 s100, s8
	s_lshl_b32 s27, s8, 12
	s_add_u32 s28, s6, s27
	s_addc_u32 s29, s7, 0
	global_load_dwordx4 v[66:69], v175, s[28:29]
	global_load_dwordx4 v[70:73], v175, s[28:29] offset:1024
	global_load_dwordx4 v[74:77], v175, s[28:29] offset:2048
	global_load_dwordx4 v[78:81], v175, s[28:29] offset:3072
	s_lshl_b32 s34, s8, 7
	s_add_u32 s30, s20, s34
	s_addc_u32 s31, s21, 0
	global_load_dword v173, v176, s[30:31] sc1
	global_load_dword v174, v177, s[30:31] sc1
	s_add_u32 s28, s10, s27
	s_addc_u32 s29, s11, 0
	global_load_dwordx4 v[98:101], v175, s[28:29]
	global_load_dwordx4 v[102:105], v175, s[28:29] offset:1024
	global_load_dwordx4 v[106:109], v175, s[28:29] offset:2048
	global_load_dwordx4 v[110:113], v175, s[28:29] offset:3072
	s_add_i32 s26, s8, 1
	s_min_i32 s26, s26, s9
	s_lshl_b32 s27, s26, 12
	s_add_u32 s28, s6, s27
	s_addc_u32 s29, s7, 0
	global_load_dwordx4 v[130:133], v175, s[28:29]
	global_load_dwordx4 v[134:137], v175, s[28:29] offset:1024
	global_load_dwordx4 v[182:185], v175, s[28:29] offset:2048
	global_load_dwordx4 v[186:189], v175, s[28:29] offset:3072
	v_mov_b32_e32 v2, 0
	v_mov_b32_e32 v3, 0
	v_mov_b32_e32 v4, 0
	v_mov_b32_e32 v5, 0
	v_mov_b32_e32 v6, 0
	v_mov_b32_e32 v7, 0
	v_mov_b32_e32 v8, 0
	v_mov_b32_e32 v9, 0
	v_mov_b32_e32 v10, 0
	v_mov_b32_e32 v11, 0
	v_mov_b32_e32 v12, 0
	v_mov_b32_e32 v13, 0
	v_mov_b32_e32 v14, 0
	v_mov_b32_e32 v15, 0
	v_mov_b32_e32 v16, 0
	v_mov_b32_e32 v17, 0
	v_mov_b32_e32 v18, 0
	v_mov_b32_e32 v19, 0
	v_mov_b32_e32 v20, 0
	v_mov_b32_e32 v21, 0
	v_mov_b32_e32 v22, 0
	v_mov_b32_e32 v23, 0
	v_mov_b32_e32 v24, 0
	v_mov_b32_e32 v25, 0
	v_mov_b32_e32 v26, 0
	v_mov_b32_e32 v27, 0
	v_mov_b32_e32 v28, 0
	v_mov_b32_e32 v29, 0
	v_mov_b32_e32 v30, 0
	v_mov_b32_e32 v31, 0
	v_mov_b32_e32 v32, 0
	v_mov_b32_e32 v33, 0
	v_mov_b32_e32 v198, 0
	v_mov_b32_e32 v199, 0
	v_mov_b32_e32 v200, 0
	v_mov_b32_e32 v201, 0
	v_mov_b32_e32 v202, 0
	v_mov_b32_e32 v203, 0
	v_mov_b32_e32 v204, 0
	v_mov_b32_e32 v205, 0
	v_mov_b32_e32 v206, 0
	v_mov_b32_e32 v207, 0
	v_mov_b32_e32 v208, 0
	v_mov_b32_e32 v209, 0
	v_mov_b32_e32 v210, 0
	v_mov_b32_e32 v211, 0
	v_mov_b32_e32 v212, 0
	v_mov_b32_e32 v213, 0
	v_mov_b32_e32 v220, 0
	v_mov_b32_e32 v221, 0
	v_mov_b32_e32 v222, 0
	v_mov_b32_e32 v223, 0
	v_mov_b32_e32 v224, 0
	v_mov_b32_e32 v225, 0
	v_mov_b32_e32 v226, 0
	v_mov_b32_e32 v227, 0
	v_mov_b32_e32 v228, 0
	v_mov_b32_e32 v229, 0
	v_mov_b32_e32 v230, 0
	v_mov_b32_e32 v231, 0
	v_mov_b32_e32 v232, 0
	v_mov_b32_e32 v233, 0
	v_mov_b32_e32 v234, 0
	v_mov_b32_e32 v235, 0
	v_mov_b32_e32 v167, 0
	v_mov_b32_e32 v169, 0
	v_mov_b32_e32 v168, 0
	v_mov_b32_e32 v170, 0
	v_mov_b32_e32 v140, 0
	v_mov_b32_e32 v141, 0
	v_mov_b32_e32 v142, 0
	v_mov_b32_e32 v143, 0
	v_mov_b32_e32 v152, 0
	v_mov_b32_e32 v153, 0
	v_mov_b32_e32 v154, 0
	v_mov_b32_e32 v155, 0
	v_mov_b32_e32 v214, 0
	v_mov_b32_e32 v215, 0
	v_mov_b32_e32 v216, 0
	v_mov_b32_e32 v217, 0
	v_mov_b32_e32 v236, 0
	v_mov_b32_e32 v237, 0
	v_mov_b32_e32 v238, 0
	v_mov_b32_e32 v239, 0
	v_mov_b32_e32 v50, 0
	v_mov_b32_e32 v51, 0
	v_mov_b32_e32 v52, 0
	v_mov_b32_e32 v53, 0
	v_mov_b32_e32 v54, 0
	v_mov_b32_e32 v55, 0
	v_mov_b32_e32 v56, 0
	v_mov_b32_e32 v57, 0
	s_waitcnt vmcnt(10)
	v_mfma_f32_32x32x16_bf16 v[34:49], v[66:69], v[82:85], 0
	v_mfma_f32_32x32x16_bf16 v[34:49], v[70:73], v[86:89], v[34:49]
	v_mfma_f32_32x32x16_bf16 v[34:49], v[74:77], v[90:93], v[34:49]
	v_mfma_f32_32x32x16_bf16 v[34:49], v[78:81], v[94:97], v[34:49]
; __device__ __forceinline__ void attn_phase(const bf16_t* Z, const bf16_t* Kb, const bf16_t* Vb, unsigned* MASKb, unsigned* itemcnt, bf16_t* Y, LAS unsigned char* lds, int wave, int lane, int bid, int G) {
;     ...
;             if (tb < te) ATT_LOAD(kA, vA, mA, tb);
;             for (int kt = tb; kt < te; kt += 2) {
;                 { const int k1 = (kt + 1 < te) ? kt + 1 : kt; ATT_LOAD(kB, vB, mB, k1); }
;                 ATT_COMP(kA, vA, mA);
;                 { const int k2 = (kt + 2 < te) ? kt + 2 : te - 1; ATT_LOAD(kA, vA, mA, k2); }
;                 if (kt + 1 < te) ATT_COMP(kB, vB, mB);
.Lat_pb0:
	s_waitcnt vmcnt(8)
	v_mfma_f32_32x32x16_bf16 v[198:213], v[140:143], v[50:53], v[198:213]
	v_lshrrev_b32_e32 v171, v139, v173
	v_lshrrev_b32_e32 v172, v139, v174
	s_add_i32 s26, s8, 1
	s_min_i32 s26, s26, s9
	v_mfma_f32_32x32x16_bf16 v[220:235], v[214:217], v[50:53], v[220:235]
	s_lshl_b32 s27, s26, 12
	s_lshl_b32 s34, s26, 7
	s_add_u32 s30, s20, s34
	s_addc_u32 s31, s21, 0
	v_mfma_f32_32x32x16_bf16 v[198:213], v[152:155], v[54:57], v[198:213]
	s_add_u32 s28, s10, s27
	s_addc_u32 s29, s11, 0
	s_cmp_gt_u32 s8, s35
	s_cselect_b32 s82, 0, -1
	v_mfma_f32_32x32x16_bf16 v[220:235], v[236:239], v[54:57], v[220:235]
	v_and_b32_e32 v171, s82, v171
	global_load_dword v173, v176, s[30:31] sc1
	global_load_dword v174, v177, s[30:31] sc1
	global_load_dwordx4 v[140:143], v175, s[28:29]
	global_load_dwordx4 v[152:155], v175, s[28:29] offset:1024
	global_load_dwordx4 v[214:217], v175, s[28:29] offset:2048
	global_load_dwordx4 v[236:239], v175, s[28:29] offset:3072
	v_mfma_f32_32x32x16_bf16 v[50:65], v[66:69], v[114:117], 0
	v_bfe_i32 v178, v171, 0, 1
	v_bitop3_b32 v34, v34, s96, v178 bitop3:0xe4
	v_bfe_i32 v180, v171, 1, 1
	v_bitop3_b32 v35, v35, s96, v180 bitop3:0xe4
	v_bfe_i32 v178, v171, 2, 1
	v_bitop3_b32 v36, v36, s96, v178 bitop3:0xe4
	v_bfe_i32 v180, v171, 3, 1
	v_bitop3_b32 v37, v37, s96, v180 bitop3:0xe4
	v_bfe_i32 v178, v171, 8, 1
	v_mfma_f32_32x32x16_bf16 v[50:65], v[70:73], v[118:121], v[50:65]
	v_bitop3_b32 v38, v38, s96, v178 bitop3:0xe4
	v_bfe_i32 v180, v171, 9, 1
	v_bitop3_b32 v39, v39, s96, v180 bitop3:0xe4
	v_bfe_i32 v178, v171, 10, 1
	v_bitop3_b32 v40, v40, s96, v178 bitop3:0xe4
	v_bfe_i32 v180, v171, 11, 1
	v_bitop3_b32 v41, v41, s96, v180 bitop3:0xe4
	v_bfe_i32 v178, v171, 16, 1
	v_bitop3_b32 v42, v42, s96, v178 bitop3:0xe4
	v_mfma_f32_32x32x16_bf16 v[50:65], v[74:77], v[122:125], v[50:65]
	v_bfe_i32 v180, v171, 17, 1
	v_bitop3_b32 v43, v43, s96, v180 bitop3:0xe4
	v_bfe_i32 v178, v171, 18, 1
	v_bitop3_b32 v44, v44, s96, v178 bitop3:0xe4
	v_bfe_i32 v180, v171, 19, 1
	v_bitop3_b32 v45, v45, s96, v180 bitop3:0xe4
	v_bfe_i32 v178, v171, 24, 1
	v_bitop3_b32 v46, v46, s96, v178 bitop3:0xe4
	v_bfe_i32 v180, v171, 25, 1
	v_mfma_f32_32x32x16_bf16 v[50:65], v[78:81], v[126:129], v[50:65]
	v_bitop3_b32 v47, v47, s96, v180 bitop3:0xe4
	v_bfe_i32 v178, v171, 26, 1
	v_bitop3_b32 v48, v48, s96, v178 bitop3:0xe4
	v_bfe_i32 v180, v171, 27, 1
	v_bitop3_b32 v49, v49, s96, v180 bitop3:0xe4
	s_add_i32 s26, s8, 2
	s_min_i32 s26, s26, s9
	s_lshl_b32 s27, s26, 12
	s_add_u32 s26, s6, s27
	s_addc_u32 s27, s7, 0
	global_load_dwordx4 v[66:69], v175, s[26:27]
	global_load_dwordx4 v[70:73], v175, s[26:27] offset:1024
	global_load_dwordx4 v[74:77], v175, s[26:27] offset:2048
	global_load_dwordx4 v[78:81], v175, s[26:27] offset:3072
	v_exp_f32_e32 v34, v34
	v_exp_f32_e32 v35, v35
	v_exp_f32_e32 v36, v36
	v_add_f32_e32 v196, v34, v35
	v_exp_f32_e32 v37, v37
	v_add_f32_e32 v196, v196, v36
	v_exp_f32_e32 v38, v38
	v_add_f32_e32 v196, v196, v37
	v_exp_f32_e32 v39, v39
	v_add_f32_e32 v196, v196, v38
	v_exp_f32_e32 v40, v40
	v_add_f32_e32 v196, v196, v39
	v_exp_f32_e32 v41, v41
	v_add_f32_e32 v196, v196, v40
	v_exp_f32_e32 v42, v42
	v_add_f32_e32 v196, v196, v41
	v_exp_f32_e32 v43, v43
	v_add_f32_e32 v196, v196, v42
	v_exp_f32_e32 v44, v44
	v_add_f32_e32 v196, v196, v43
	v_exp_f32_e32 v45, v45
	v_add_f32_e32 v196, v196, v44
	v_exp_f32_e32 v46, v46
	v_add_f32_e32 v196, v196, v45
	v_exp_f32_e32 v47, v47
	v_add_f32_e32 v196, v196, v46
	v_exp_f32_e32 v48, v48
	v_add_f32_e32 v196, v196, v47
	v_exp_f32_e32 v49, v49
	v_add_f32_e32 v196, v196, v48
	s_nop 0
	v_add_f32_e32 v196, v196, v49
	v_add_f32_e32 v167, v167, v196
	v_cvt_pk_bf16_f32 v34, v34, v35
	v_cvt_pk_bf16_f32 v35, v36, v37
	v_cvt_pk_bf16_f32 v36, v38, v39
	v_cvt_pk_bf16_f32 v37, v40, v41
	v_cvt_pk_bf16_f32 v38, v42, v43
	v_cvt_pk_bf16_f32 v39, v44, v45
	v_cvt_pk_bf16_f32 v40, v46, v47
	v_cvt_pk_bf16_f32 v41, v48, v49
	s_waitcnt vmcnt(14)
	v_bfe_i32 v178, v172, 0, 1
	v_bitop3_b32 v50, v50, s96, v178 bitop3:0xe4
	v_mfma_f32_32x32x16_bf16 v[18:33], v[98:101], v[34:37], v[18:33]
	v_bfe_i32 v180, v172, 1, 1
	v_bitop3_b32 v51, v51, s96, v180 bitop3:0xe4
	v_bfe_i32 v178, v172, 2, 1
	v_bitop3_b32 v52, v52, s96, v178 bitop3:0xe4
	v_bfe_i32 v180, v172, 3, 1
	v_bitop3_b32 v53, v53, s96, v180 bitop3:0xe4
	v_bfe_i32 v178, v172, 8, 1
	v_bitop3_b32 v54, v54, s96, v178 bitop3:0xe4
	v_mfma_f32_32x32x16_bf16 v[2:17], v[106:109], v[34:37], v[2:17]
	v_bfe_i32 v180, v172, 9, 1
	v_bitop3_b32 v55, v55, s96, v180 bitop3:0xe4
	v_bfe_i32 v178, v172, 10, 1
	v_bitop3_b32 v56, v56, s96, v178 bitop3:0xe4
	v_bfe_i32 v180, v172, 11, 1
	v_bitop3_b32 v57, v57, s96, v180 bitop3:0xe4
	v_bfe_i32 v178, v172, 16, 1
	v_bitop3_b32 v58, v58, s96, v178 bitop3:0xe4
	v_mfma_f32_32x32x16_bf16 v[18:33], v[102:105], v[38:41], v[18:33]
	v_bfe_i32 v180, v172, 17, 1
	v_bitop3_b32 v59, v59, s96, v180 bitop3:0xe4
	v_bfe_i32 v178, v172, 18, 1
	v_bitop3_b32 v60, v60, s96, v178 bitop3:0xe4
	v_bfe_i32 v180, v172, 19, 1
	v_bitop3_b32 v61, v61, s96, v180 bitop3:0xe4
	v_bfe_i32 v178, v172, 24, 1
	v_bitop3_b32 v62, v62, s96, v178 bitop3:0xe4
	v_mfma_f32_32x32x16_bf16 v[2:17], v[110:113], v[38:41], v[2:17]
	v_bfe_i32 v180, v172, 25, 1
	v_bitop3_b32 v63, v63, s96, v180 bitop3:0xe4
	v_bfe_i32 v178, v172, 26, 1
	v_bitop3_b32 v64, v64, s96, v178 bitop3:0xe4
	v_bfe_i32 v180, v172, 27, 1
	v_bitop3_b32 v65, v65, s96, v180 bitop3:0xe4
	v_exp_f32_e32 v50, v50
	s_waitcnt vmcnt(10)
	v_mfma_f32_32x32x16_bf16 v[34:49], v[130:133], v[82:85], 0
	v_exp_f32_e32 v51, v51
	v_exp_f32_e32 v52, v52
	v_add_f32_e32 v196, v50, v51
	v_exp_f32_e32 v53, v53
	v_add_f32_e32 v196, v196, v52
	v_exp_f32_e32 v54, v54
	v_add_f32_e32 v196, v196, v53
	v_exp_f32_e32 v55, v55
	v_mfma_f32_32x32x16_bf16 v[34:49], v[134:137], v[86:89], v[34:49]
	v_add_f32_e32 v196, v196, v54
	v_exp_f32_e32 v56, v56
	v_add_f32_e32 v196, v196, v55
	v_exp_f32_e32 v57, v57
	v_add_f32_e32 v196, v196, v56
	v_exp_f32_e32 v58, v58
	v_add_f32_e32 v196, v196, v57
	v_exp_f32_e32 v59, v59
	v_mfma_f32_32x32x16_bf16 v[34:49], v[182:185], v[90:93], v[34:49]
	v_add_f32_e32 v196, v196, v58
	v_exp_f32_e32 v60, v60
	v_add_f32_e32 v196, v196, v59
	v_exp_f32_e32 v61, v61
	v_add_f32_e32 v196, v196, v60
	v_exp_f32_e32 v62, v62
	v_add_f32_e32 v196, v196, v61
	v_exp_f32_e32 v63, v63
	v_mfma_f32_32x32x16_bf16 v[34:49], v[186:189], v[94:97], v[34:49]
	v_add_f32_e32 v196, v196, v62
	v_exp_f32_e32 v64, v64
	v_add_f32_e32 v196, v196, v63
	v_exp_f32_e32 v65, v65
	v_add_f32_e32 v196, v196, v64
	s_nop 0
	v_add_f32_e32 v196, v196, v65
	v_add_f32_e32 v169, v169, v196
	v_cvt_pk_bf16_f32 v50, v50, v51
	v_cvt_pk_bf16_f32 v51, v52, v53
	v_cvt_pk_bf16_f32 v52, v54, v55
	v_cvt_pk_bf16_f32 v53, v56, v57
	v_cvt_pk_bf16_f32 v54, v58, v59
	v_cvt_pk_bf16_f32 v55, v60, v61
	v_cvt_pk_bf16_f32 v56, v62, v63
	v_cvt_pk_bf16_f32 v57, v64, v65
	s_add_i32 s8, s8, 1
	s_cmp_lt_i32 s8, s19
	s_cbranch_scc0 .Lat_px0
; __device__ __forceinline__ void attn_phase(const bf16_t* Z, const bf16_t* Kb, const bf16_t* Vb, unsigned* MASKb, unsigned* itemcnt, bf16_t* Y, LAS unsigned char* lds, int wave, int lane, int bid, int G) {
;     ...
;             if (tb < te) ATT_LOAD(kA, vA, mA, tb);
;             for (int kt = tb; kt < te; kt += 2) {
;                 { const int k1 = (kt + 1 < te) ? kt + 1 : kt; ATT_LOAD(kB, vB, mB, k1); }
;                 ATT_COMP(kA, vA, mA);
;                 { const int k2 = (kt + 2 < te) ? kt + 2 : te - 1; ATT_LOAD(kA, vA, mA, k2); }
;                 if (kt + 1 < te) ATT_COMP(kB, vB, mB);
.Lat_pb1:
	s_waitcnt vmcnt(8)
	v_mfma_f32_32x32x16_bf16 v[198:213], v[98:101], v[50:53], v[198:213]
	v_lshrrev_b32_e32 v171, v139, v173
	v_lshrrev_b32_e32 v172, v139, v174
	s_add_i32 s26, s8, 1
	s_min_i32 s26, s26, s9
	v_mfma_f32_32x32x16_bf16 v[220:235], v[106:109], v[50:53], v[220:235]
	s_lshl_b32 s27, s26, 12
	s_lshl_b32 s34, s26, 7
	s_add_u32 s30, s20, s34
	s_addc_u32 s31, s21, 0
	v_mfma_f32_32x32x16_bf16 v[198:213], v[102:105], v[54:57], v[198:213]
	s_add_u32 s28, s10, s27
	s_addc_u32 s29, s11, 0
	s_cmp_gt_u32 s8, s35
	s_cselect_b32 s82, 0, -1
	v_mfma_f32_32x32x16_bf16 v[220:235], v[110:113], v[54:57], v[220:235]
	v_and_b32_e32 v171, s82, v171
	global_load_dword v173, v176, s[30:31] sc1
	global_load_dword v174, v177, s[30:31] sc1
	global_load_dwordx4 v[98:101], v175, s[28:29]
	global_load_dwordx4 v[102:105], v175, s[28:29] offset:1024
	global_load_dwordx4 v[106:109], v175, s[28:29] offset:2048
	global_load_dwordx4 v[110:113], v175, s[28:29] offset:3072
	v_mfma_f32_32x32x16_bf16 v[50:65], v[130:133], v[114:117], 0
	v_bfe_i32 v178, v171, 0, 1
	v_bitop3_b32 v34, v34, s96, v178 bitop3:0xe4
	v_bfe_i32 v180, v171, 1, 1
	v_bitop3_b32 v35, v35, s96, v180 bitop3:0xe4
	v_bfe_i32 v178, v171, 2, 1
	v_bitop3_b32 v36, v36, s96, v178 bitop3:0xe4
	v_bfe_i32 v180, v171, 3, 1
	v_bitop3_b32 v37, v37, s96, v180 bitop3:0xe4
	v_bfe_i32 v178, v171, 8, 1
	v_mfma_f32_32x32x16_bf16 v[50:65], v[134:137], v[118:121], v[50:65]
	v_bitop3_b32 v38, v38, s96, v178 bitop3:0xe4
	v_bfe_i32 v180, v171, 9, 1
	v_bitop3_b32 v39, v39, s96, v180 bitop3:0xe4
	v_bfe_i32 v178, v171, 10, 1
	v_bitop3_b32 v40, v40, s96, v178 bitop3:0xe4
	v_bfe_i32 v180, v171, 11, 1
	v_bitop3_b32 v41, v41, s96, v180 bitop3:0xe4
	v_bfe_i32 v178, v171, 16, 1
	v_bitop3_b32 v42, v42, s96, v178 bitop3:0xe4
	v_mfma_f32_32x32x16_bf16 v[50:65], v[182:185], v[122:125], v[50:65]
	v_bfe_i32 v180, v171, 17, 1
	v_bitop3_b32 v43, v43, s96, v180 bitop3:0xe4
	v_bfe_i32 v178, v171, 18, 1
	v_bitop3_b32 v44, v44, s96, v178 bitop3:0xe4
	v_bfe_i32 v180, v171, 19, 1
	v_bitop3_b32 v45, v45, s96, v180 bitop3:0xe4
	v_bfe_i32 v178, v171, 24, 1
	v_bitop3_b32 v46, v46, s96, v178 bitop3:0xe4
	v_bfe_i32 v180, v171, 25, 1
	v_mfma_f32_32x32x16_bf16 v[50:65], v[186:189], v[126:129], v[50:65]
	v_bitop3_b32 v47, v47, s96, v180 bitop3:0xe4
	v_bfe_i32 v178, v171, 26, 1
	v_bitop3_b32 v48, v48, s96, v178 bitop3:0xe4
	v_bfe_i32 v180, v171, 27, 1
	v_bitop3_b32 v49, v49, s96, v180 bitop3:0xe4
	s_add_i32 s26, s8, 2
	s_min_i32 s26, s26, s9
	s_lshl_b32 s27, s26, 12
	s_add_u32 s26, s6, s27
	s_addc_u32 s27, s7, 0
	global_load_dwordx4 v[130:133], v175, s[26:27]
	global_load_dwordx4 v[134:137], v175, s[26:27] offset:1024
	global_load_dwordx4 v[182:185], v175, s[26:27] offset:2048
	global_load_dwordx4 v[186:189], v175, s[26:27] offset:3072
	v_exp_f32_e32 v34, v34
	v_exp_f32_e32 v35, v35
	v_exp_f32_e32 v36, v36
	v_add_f32_e32 v196, v34, v35
	v_exp_f32_e32 v37, v37
	v_add_f32_e32 v196, v196, v36
	v_exp_f32_e32 v38, v38
	v_add_f32_e32 v196, v196, v37
	v_exp_f32_e32 v39, v39
	v_add_f32_e32 v196, v196, v38
	v_exp_f32_e32 v40, v40
	v_add_f32_e32 v196, v196, v39
	v_exp_f32_e32 v41, v41
	v_add_f32_e32 v196, v196, v40
	v_exp_f32_e32 v42, v42
	v_add_f32_e32 v196, v196, v41
	v_exp_f32_e32 v43, v43
	v_add_f32_e32 v196, v196, v42
	v_exp_f32_e32 v44, v44
	v_add_f32_e32 v196, v196, v43
	v_exp_f32_e32 v45, v45
	v_add_f32_e32 v196, v196, v44
	v_exp_f32_e32 v46, v46
	v_add_f32_e32 v196, v196, v45
	v_exp_f32_e32 v47, v47
	v_add_f32_e32 v196, v196, v46
	v_exp_f32_e32 v48, v48
	v_add_f32_e32 v196, v196, v47
	v_exp_f32_e32 v49, v49
	v_add_f32_e32 v196, v196, v48
	s_nop 0
	v_add_f32_e32 v196, v196, v49
	v_add_f32_e32 v167, v167, v196
	v_cvt_pk_bf16_f32 v34, v34, v35
	v_cvt_pk_bf16_f32 v35, v36, v37
	v_cvt_pk_bf16_f32 v36, v38, v39
	v_cvt_pk_bf16_f32 v37, v40, v41
	v_cvt_pk_bf16_f32 v38, v42, v43
	v_cvt_pk_bf16_f32 v39, v44, v45
	v_cvt_pk_bf16_f32 v40, v46, v47
	v_cvt_pk_bf16_f32 v41, v48, v49
	s_waitcnt vmcnt(14)
	v_bfe_i32 v178, v172, 0, 1
	v_bitop3_b32 v50, v50, s96, v178 bitop3:0xe4
	v_mfma_f32_32x32x16_bf16 v[18:33], v[140:143], v[34:37], v[18:33]
	v_bfe_i32 v180, v172, 1, 1
	v_bitop3_b32 v51, v51, s96, v180 bitop3:0xe4
	v_bfe_i32 v178, v172, 2, 1
	v_bitop3_b32 v52, v52, s96, v178 bitop3:0xe4
	v_bfe_i32 v180, v172, 3, 1
	v_bitop3_b32 v53, v53, s96, v180 bitop3:0xe4
	v_bfe_i32 v178, v172, 8, 1
	v_bitop3_b32 v54, v54, s96, v178 bitop3:0xe4
	v_mfma_f32_32x32x16_bf16 v[2:17], v[214:217], v[34:37], v[2:17]
	v_bfe_i32 v180, v172, 9, 1
	v_bitop3_b32 v55, v55, s96, v180 bitop3:0xe4
	v_bfe_i32 v178, v172, 10, 1
	v_bitop3_b32 v56, v56, s96, v178 bitop3:0xe4
	v_bfe_i32 v180, v172, 11, 1
	v_bitop3_b32 v57, v57, s96, v180 bitop3:0xe4
	v_bfe_i32 v178, v172, 16, 1
	v_bitop3_b32 v58, v58, s96, v178 bitop3:0xe4
	v_mfma_f32_32x32x16_bf16 v[18:33], v[152:155], v[38:41], v[18:33]
	v_bfe_i32 v180, v172, 17, 1
	v_bitop3_b32 v59, v59, s96, v180 bitop3:0xe4
	v_bfe_i32 v178, v172, 18, 1
	v_bitop3_b32 v60, v60, s96, v178 bitop3:0xe4
	v_bfe_i32 v180, v172, 19, 1
	v_bitop3_b32 v61, v61, s96, v180 bitop3:0xe4
	v_bfe_i32 v178, v172, 24, 1
	v_bitop3_b32 v62, v62, s96, v178 bitop3:0xe4
	v_mfma_f32_32x32x16_bf16 v[2:17], v[236:239], v[38:41], v[2:17]
	v_bfe_i32 v180, v172, 25, 1
	v_bitop3_b32 v63, v63, s96, v180 bitop3:0xe4
	v_bfe_i32 v178, v172, 26, 1
	v_bitop3_b32 v64, v64, s96, v178 bitop3:0xe4
	v_bfe_i32 v180, v172, 27, 1
	v_bitop3_b32 v65, v65, s96, v180 bitop3:0xe4
	v_exp_f32_e32 v50, v50
	s_waitcnt vmcnt(10)
	v_mfma_f32_32x32x16_bf16 v[34:49], v[66:69], v[82:85], 0
	v_exp_f32_e32 v51, v51
	v_exp_f32_e32 v52, v52
	v_add_f32_e32 v196, v50, v51
	v_exp_f32_e32 v53, v53
	v_add_f32_e32 v196, v196, v52
	v_exp_f32_e32 v54, v54
	v_add_f32_e32 v196, v196, v53
	v_exp_f32_e32 v55, v55
	v_mfma_f32_32x32x16_bf16 v[34:49], v[70:73], v[86:89], v[34:49]
	v_add_f32_e32 v196, v196, v54
	v_exp_f32_e32 v56, v56
	v_add_f32_e32 v196, v196, v55
	v_exp_f32_e32 v57, v57
	v_add_f32_e32 v196, v196, v56
	v_exp_f32_e32 v58, v58
	v_add_f32_e32 v196, v196, v57
	v_exp_f32_e32 v59, v59
	v_mfma_f32_32x32x16_bf16 v[34:49], v[74:77], v[90:93], v[34:49]
	v_add_f32_e32 v196, v196, v58
	v_exp_f32_e32 v60, v60
	v_add_f32_e32 v196, v196, v59
	v_exp_f32_e32 v61, v61
	v_add_f32_e32 v196, v196, v60
	v_exp_f32_e32 v62, v62
	v_add_f32_e32 v196, v196, v61
	v_exp_f32_e32 v63, v63
	v_mfma_f32_32x32x16_bf16 v[34:49], v[78:81], v[94:97], v[34:49]
	v_add_f32_e32 v196, v196, v62
	v_exp_f32_e32 v64, v64
	v_add_f32_e32 v196, v196, v63
	v_exp_f32_e32 v65, v65
	v_add_f32_e32 v196, v196, v64
	s_nop 0
	v_add_f32_e32 v196, v196, v65
	v_add_f32_e32 v169, v169, v196
	v_cvt_pk_bf16_f32 v50, v50, v51
	v_cvt_pk_bf16_f32 v51, v52, v53
	v_cvt_pk_bf16_f32 v52, v54, v55
	v_cvt_pk_bf16_f32 v53, v56, v57
	v_cvt_pk_bf16_f32 v54, v58, v59
	v_cvt_pk_bf16_f32 v55, v60, v61
	v_cvt_pk_bf16_f32 v56, v62, v63
	v_cvt_pk_bf16_f32 v57, v64, v65
	s_add_i32 s8, s8, 1
	s_cmp_lt_i32 s8, s19
	s_cbranch_scc1 .Lat_pb0
; __device__ __forceinline__ float swap32(float v, int hi) { auto rr = __builtin_amdgcn_permlane32_swap(__float_as_uint(v), __float_as_uint(v), false, false); return hi ? __uint_as_float(rr[0]) : __uint_as_float(rr[1]); }
; __device__ __forceinline__ void attn_phase(const bf16_t* Z, const bf16_t* Kb, const bf16_t* Vb, unsigned* MASKb, unsigned* itemcnt, bf16_t* Y, LAS unsigned char* lds, int wave, int lane, int bid, int G) {
;     ...
;             for (int kt = tb; kt < te; kt += 2) {
;                 { const int k1 = (kt + 1 < te) ? kt + 1 : kt; ATT_LOAD(kB, vB, mB, k1); }
;                 ATT_COMP(kA, vA, mA);
;                 { const int k2 = (kt + 2 < te) ? kt + 2 : te - 1; ATT_LOAD(kA, vA, mA, k2); }
;                 if (kt + 1 < te) ATT_COMP(kB, vB, mB);
;             }
;     ...
;             const float lt = l + swap32(l, hi);
	v_mfma_f32_32x32x16_bf16 v[198:213], v[140:143], v[50:53], v[198:213]
	v_mfma_f32_32x32x16_bf16 v[220:235], v[214:217], v[50:53], v[220:235]
	v_mfma_f32_32x32x16_bf16 v[198:213], v[152:155], v[54:57], v[198:213]
	v_mfma_f32_32x32x16_bf16 v[220:235], v[236:239], v[54:57], v[220:235]
	s_branch .Lat_pxd
.Lat_px0:
	v_mfma_f32_32x32x16_bf16 v[198:213], v[98:101], v[50:53], v[198:213]
	v_mfma_f32_32x32x16_bf16 v[220:235], v[106:109], v[50:53], v[220:235]
	v_mfma_f32_32x32x16_bf16 v[198:213], v[102:105], v[54:57], v[198:213]
	v_mfma_f32_32x32x16_bf16 v[220:235], v[110:113], v[54:57], v[220:235]
.Lat_pxd:
	s_waitcnt vmcnt(0)
	s_movk_i32 s26, 0x207
	v_cmp_class_f32_e64 vcc, v167, s26
	s_cbranch_vccnz .Lat_safe
	v_cmp_class_f32_e64 vcc, v169, s26
	s_cbranch_vccz .Lat_epi0
